# P1 K-loop: first half-iteration after an epilogue peeled with vmcnt(24) so epilogue stores drain under MFMAs; dropped 8 conservative vmcnt(0)
# baseline (speedup 1.0000x reference)
; #define PG8_STAGE(bufoff, gbase, voff) do { _Pragma("unroll") for (int _i = 0; _i < 2; ++_i) \
;         __builtin_amdgcn_global_load_lds((const unsigned*)((const char*)(gbase) + (voff)[_i]), (LAS unsigned*)(lds + (bufoff) + ldsw + _i * 8192), 16, 0, 0); } while (0)
; #define PG8_LDA(dst, b, h) do { _Pragma("unroll") for (int m = 0; m < 4; ++m) _Pragma("unroll") for (int k = 0; k < 2; ++k) dst[m][k] = *(const LAS bf16x8*)(lds + PG8_SA(b, h) + aoff + m * 2048 + k * 1024); } while (0)
; #define PG8_LDB(dst, b, h) do { _Pragma("unroll") for (int n = 0; n < 2; ++n) _Pragma("unroll") for (int k = 0; k < 2; ++k) dst[n][k] = *(const LAS bf16x8*)(lds + PG8_SB(b, h) + boff + n * 2048 + k * 1024); } while (0)
; #define PG8_WAIT_V(n) asm volatile("s_waitcnt vmcnt(" #n ")" ::: "memory")
; #define PG8_WAIT_L(n) asm volatile("s_waitcnt lgkmcnt(" #n ")" ::: "memory")
; #define PG8_BAR __builtin_amdgcn_s_barrier()
; #define PG8_SCHED __builtin_amdgcn_sched_barrier(0)
; template <class Epi, int AC0, int BC0, int NT0, int AC1, int BC1, int NT1>
; __device__ __forceinline__ void gemm_phase(LAS unsigned char* lds, const Gemm g, const StaticOrder& S, const Epi& E, int tid) {
;     ...
;         const char* nA = has_next ? PG8_APTR(nxt) : cA; const char* nB = has_next ? PG8_BPTR(nxt) : cB;
;         const int nt = NT0 + cur.seg * (NT1 - NT0);
;         for (int t = 0; t < nt; t += 2) {
;             const bool last = (t == nt - 2);
;             const char* a1 = cA + (size_t)(t + 1) * kstep;
;             const char* a2 = last ? nA : cA + (size_t)(t + 2) * kstep; const char* b2 = last ? nB : cB + (size_t)(t + 2) * kstep;
;             const char* a3 = a2 + kstep; const char* b3 = b2 + kstep;
;             PG8_LDB(B0, 0, 0); PG8_LDB(B1, 0, 1); PG8_SCHED; PG8_LDA(At, 0, 0); PG8_STAGE(PG8_SA(1, 1), a1 + hstepA, voffA);
;             PG8_WAIT_V(8); PG8_WAIT_L(0); PG8_BAR; PG8_MMA(0, 0, At, B0); PG8_MMA(0, 1, At, B1); PG8_BAR; PG8_SCHED;
;     ...
;         if (!(Epi::KEEP0 && cur.seg == 0)) {
; #pragma unroll
;             for (int a = 0; a < 2; ++a)
; #pragma unroll
;                 for (int b = 0; b < 2; ++b)
; #pragma unroll
;                     for (int m = 0; m < 4; ++m)
; #pragma unroll
;                         for (int n = 0; n < 2; ++n) acc[a][b][m][n] = (f32x4){0.f, 0.f, 0.f, 0.f};
;         }
;         cur = nxt; cA = nA; cB = nB; ++ui;
.LBB0_123:
	s_ashr_i32 s29, s28, 31
	s_lshl_b64 s[12:13], s[28:29], 19
	s_add_u32 s30, s80, s12
	s_addc_u32 s31, s81, s13
	s_and_b64 s[12:13], s[4:5], exec
	s_cselect_b32 s3, s31, s1
	s_cselect_b32 s9, s30, s0
	s_ashr_i32 s27, s26, 31
	s_lshl_b64 s[12:13], s[26:27], 19
	v_readlane_b32 s34, v254, 4
	v_readlane_b32 s35, v254, 5
	s_add_u32 s34, s34, s12
	s_addc_u32 s35, s35, s13
	s_and_b64 s[12:13], s[4:5], exec
	s_cselect_b32 s11, s35, s7
	s_cselect_b32 s15, s34, s6
	s_add_u32 s0, s0, 0x40080
	s_addc_u32 s1, s1, 0
	s_add_u32 s16, s6, 0x100
	v_mov_b32_e32 v2, 0
	s_addc_u32 s22, s7, 0
	s_mov_b32 s27, -2
	v_mov_b32_e32 v3, v2
	v_mov_b32_e32 v4, v2
	v_mov_b32_e32 v5, v2
	v_mov_b32_e32 v6, v2
	v_mov_b32_e32 v7, v2
	v_mov_b32_e32 v8, v2
	v_mov_b32_e32 v9, v2
	v_mov_b32_e32 v18, v2
	v_mov_b32_e32 v19, v2
	v_mov_b32_e32 v20, v2
	v_mov_b32_e32 v21, v2
	v_mov_b32_e32 v22, v2
	v_mov_b32_e32 v23, v2
	v_mov_b32_e32 v24, v2
	v_mov_b32_e32 v25, v2
	v_mov_b32_e32 v50, v2
	v_mov_b32_e32 v51, v2
	v_mov_b32_e32 v52, v2
	v_mov_b32_e32 v53, v2
	v_mov_b32_e32 v54, v2
	v_mov_b32_e32 v55, v2
	v_mov_b32_e32 v56, v2
	v_mov_b32_e32 v57, v2
	v_mov_b32_e32 v66, v2
	v_mov_b32_e32 v67, v2
	v_mov_b32_e32 v68, v2
	v_mov_b32_e32 v69, v2
	v_mov_b32_e32 v70, v2
	v_mov_b32_e32 v71, v2
	v_mov_b32_e32 v72, v2
	v_mov_b32_e32 v73, v2
	v_mov_b32_e32 v10, v2
	v_mov_b32_e32 v11, v2
	v_mov_b32_e32 v12, v2
	v_mov_b32_e32 v13, v2
	v_mov_b32_e32 v14, v2
	v_mov_b32_e32 v15, v2
	v_mov_b32_e32 v16, v2
	v_mov_b32_e32 v17, v2
	v_mov_b32_e32 v34, v2
	v_mov_b32_e32 v35, v2
	v_mov_b32_e32 v36, v2
	v_mov_b32_e32 v37, v2
	v_mov_b32_e32 v38, v2
	v_mov_b32_e32 v39, v2
	v_mov_b32_e32 v40, v2
	v_mov_b32_e32 v41, v2
	v_mov_b32_e32 v58, v2
	v_mov_b32_e32 v59, v2
	v_mov_b32_e32 v60, v2
	v_mov_b32_e32 v61, v2
	v_mov_b32_e32 v62, v2
	v_mov_b32_e32 v63, v2
	v_mov_b32_e32 v64, v2
	v_mov_b32_e32 v65, v2
	v_mov_b32_e32 v74, v2
	v_mov_b32_e32 v75, v2
	v_mov_b32_e32 v76, v2
	v_mov_b32_e32 v77, v2
	v_mov_b32_e32 v78, v2
	v_mov_b32_e32 v79, v2
	v_mov_b32_e32 v80, v2
	v_mov_b32_e32 v81, v2
	v_mov_b32_e32 v82, v2
	v_mov_b32_e32 v83, v2
	v_mov_b32_e32 v84, v2
	v_mov_b32_e32 v85, v2
	v_mov_b32_e32 v86, v2
	v_mov_b32_e32 v87, v2
	v_mov_b32_e32 v88, v2
	v_mov_b32_e32 v89, v2
	v_mov_b32_e32 v98, v2
	v_mov_b32_e32 v99, v2
	v_mov_b32_e32 v100, v2
	v_mov_b32_e32 v101, v2
	v_mov_b32_e32 v102, v2
	v_mov_b32_e32 v103, v2
	v_mov_b32_e32 v104, v2
	v_mov_b32_e32 v105, v2
	v_mov_b32_e32 v114, v2
	v_mov_b32_e32 v115, v2
	v_mov_b32_e32 v116, v2
	v_mov_b32_e32 v117, v2
	v_mov_b32_e32 v118, v2
	v_mov_b32_e32 v119, v2
	v_mov_b32_e32 v120, v2
	v_mov_b32_e32 v121, v2
	v_mov_b32_e32 v130, v2
	v_mov_b32_e32 v131, v2
	v_mov_b32_e32 v132, v2
	v_mov_b32_e32 v133, v2
	v_mov_b32_e32 v134, v2
	v_mov_b32_e32 v135, v2
	v_mov_b32_e32 v136, v2
	v_mov_b32_e32 v137, v2
	v_mov_b32_e32 v90, v2
	v_mov_b32_e32 v91, v2
	v_mov_b32_e32 v92, v2
	v_mov_b32_e32 v93, v2
	v_mov_b32_e32 v94, v2
	v_mov_b32_e32 v95, v2
	v_mov_b32_e32 v96, v2
	v_mov_b32_e32 v97, v2
	v_mov_b32_e32 v106, v2
	v_mov_b32_e32 v107, v2
	v_mov_b32_e32 v108, v2
	v_mov_b32_e32 v109, v2
	v_mov_b32_e32 v110, v2
	v_mov_b32_e32 v111, v2
	v_mov_b32_e32 v112, v2
	v_mov_b32_e32 v113, v2
	v_mov_b32_e32 v122, v2
	v_mov_b32_e32 v123, v2
	v_mov_b32_e32 v124, v2
	v_mov_b32_e32 v125, v2
	v_mov_b32_e32 v126, v2
	v_mov_b32_e32 v127, v2
	v_mov_b32_e32 v128, v2
	v_mov_b32_e32 v129, v2
	v_mov_b32_e32 v138, v2
	v_mov_b32_e32 v139, v2
	v_mov_b32_e32 v140, v2
	v_mov_b32_e32 v141, v2
	v_mov_b32_e32 v142, v2
	v_mov_b32_e32 v143, v2
	v_mov_b32_e32 v144, v2
	v_mov_b32_e32 v145, v2
	s_cmp_lg_u32 s14, 1
	s_cbranch_scc0 .LBB0_124
	ds_read_b128 v[26:29], v192
	ds_read_b128 v[30:33], v192 offset:1024
	ds_read_b128 v[42:45], v192 offset:2048
	ds_read_b128 v[46:49], v192 offset:3072
	ds_read_b128 v[146:149], v193
	ds_read_b128 v[150:153], v193 offset:1024
	ds_read_b128 v[154:157], v193 offset:2048
	ds_read_b128 v[158:161], v193 offset:3072
	s_add_u32 s6, s0, 0xfffc0080
	s_addc_u32 s7, s1, -1
	s_cmp_eq_u32 s27, 12
	s_cselect_b32 s13, s3, s7
	s_cselect_b32 s12, s9, s6
	s_cselect_b32 s7, s11, s22
	s_cselect_b32 s6, s15, s16
	v_lshl_add_u64 v[186:187], s[0:1], 0, v[178:179]
	s_add_i32 m0, s95, 0xc000
	ds_read_b128 v[198:201], v194
	ds_read_b128 v[202:205], v194 offset:1024
	ds_read_b128 v[206:209], v194 offset:2048
	ds_read_b128 v[210:213], v194 offset:3072
	ds_read_b128 v[214:217], v194 offset:4096
	ds_read_b128 v[218:221], v194 offset:5120
	ds_read_b128 v[226:229], v194 offset:6144
	ds_read_b128 v[230:233], v194 offset:7168
	global_load_lds_dwordx4 v[186:187], off
	v_lshl_add_u64 v[186:187], s[0:1], 0, v[180:181]
	s_add_i32 m0, s95, 0xe000
	s_nop 0
	global_load_lds_dwordx4 v[186:187], off
	s_waitcnt vmcnt(24)
	s_waitcnt lgkmcnt(0)
	s_barrier
; #define PG8_STAGE(bufoff, gbase, voff) do { _Pragma("unroll") for (int _i = 0; _i < 2; ++_i) \
;         __builtin_amdgcn_global_load_lds((const unsigned*)((const char*)(gbase) + (voff)[_i]), (LAS unsigned*)(lds + (bufoff) + ldsw + _i * 8192), 16, 0, 0); } while (0)
; #define PG8_LDA(dst, b, h) do { _Pragma("unroll") for (int m = 0; m < 4; ++m) _Pragma("unroll") for (int k = 0; k < 2; ++k) dst[m][k] = *(const LAS bf16x8*)(lds + PG8_SA(b, h) + aoff + m * 2048 + k * 1024); } while (0)
; #define PG8_MMA(ai, bj, At, Bt) do { __builtin_amdgcn_s_setprio(1); _Pragma("unroll") for (int m = 0; m < 4; ++m) _Pragma("unroll") for (int n = 0; n < 2; ++n) _Pragma("unroll") for (int k = 0; k < 2; ++k) \
;         acc[ai][bj][m][n] = __builtin_amdgcn_mfma_f32_16x16x32_bf16(Bt[n][k], At[m][k], acc[ai][bj][m][n], 0, 0, 0); __builtin_amdgcn_s_setprio(0); } while (0)
; #define PG8_WAIT_V(n) asm volatile("s_waitcnt vmcnt(" #n ")" ::: "memory")
; #define PG8_WAIT_L(n) asm volatile("s_waitcnt lgkmcnt(" #n ")" ::: "memory")
; #define PG8_BAR __builtin_amdgcn_s_barrier()
; #define PG8_SCHED __builtin_amdgcn_sched_barrier(0)
; template <class Epi, int AC0, int BC0, int NT0, int AC1, int BC1, int NT1>
; __device__ __forceinline__ void gemm_phase(LAS unsigned char* lds, const Gemm g, const StaticOrder& S, const Epi& E, int tid) {
;     ...
;             PG8_WAIT_V(8); PG8_WAIT_L(0); PG8_BAR; PG8_MMA(0, 0, At, B0); PG8_MMA(0, 1, At, B1); PG8_BAR; PG8_SCHED;
;             PG8_LDA(At, 0, 1); PG8_STAGE(PG8_SB(0, 0), b2, voffB); PG8_STAGE(PG8_SB(0, 1), b2 + hstepB, voffB); PG8_STAGE(PG8_SA(0, 0), a2, voffA);
;             PG8_WAIT_V(8); PG8_WAIT_L(0); PG8_BAR; PG8_MMA(1, 0, At, B0); PG8_MMA(1, 1, At, B1); PG8_BAR; PG8_SCHED;
	s_setprio 1
	s_waitcnt lgkmcnt(0)
	v_mfma_f32_16x16x32_bf16 v[142:145], v[26:29], v[198:201], v[142:145]
	v_mfma_f32_16x16x32_bf16 v[138:141], v[42:45], v[198:201], v[138:141]
	v_mfma_f32_16x16x32_bf16 v[126:129], v[26:29], v[206:209], v[126:129]
	v_mfma_f32_16x16x32_bf16 v[122:125], v[42:45], v[206:209], v[122:125]
	v_mfma_f32_16x16x32_bf16 v[110:113], v[26:29], v[214:217], v[110:113]
	v_mfma_f32_16x16x32_bf16 v[106:109], v[42:45], v[214:217], v[106:109]
	v_mfma_f32_16x16x32_bf16 v[94:97], v[26:29], v[226:229], v[94:97]
	v_mfma_f32_16x16x32_bf16 v[90:93], v[42:45], v[226:229], v[90:93]
	v_mfma_f32_16x16x32_bf16 v[142:145], v[30:33], v[202:205], v[142:145]
	v_mfma_f32_16x16x32_bf16 v[138:141], v[46:49], v[202:205], v[138:141]
	v_mfma_f32_16x16x32_bf16 v[126:129], v[30:33], v[210:213], v[126:129]
	v_mfma_f32_16x16x32_bf16 v[122:125], v[46:49], v[210:213], v[122:125]
	v_mfma_f32_16x16x32_bf16 v[110:113], v[30:33], v[218:221], v[110:113]
	v_mfma_f32_16x16x32_bf16 v[106:109], v[46:49], v[218:221], v[106:109]
	v_mfma_f32_16x16x32_bf16 v[94:97], v[30:33], v[230:233], v[94:97]
	v_mfma_f32_16x16x32_bf16 v[90:93], v[46:49], v[230:233], v[90:93]
	s_setprio 0
	s_setprio 1
	v_mfma_f32_16x16x32_bf16 v[134:137], v[146:149], v[198:201], v[134:137]
	v_mfma_f32_16x16x32_bf16 v[130:133], v[154:157], v[198:201], v[130:133]
	v_mfma_f32_16x16x32_bf16 v[118:121], v[146:149], v[206:209], v[118:121]
	v_mfma_f32_16x16x32_bf16 v[114:117], v[154:157], v[206:209], v[114:117]
	v_mfma_f32_16x16x32_bf16 v[102:105], v[146:149], v[214:217], v[102:105]
	v_mfma_f32_16x16x32_bf16 v[98:101], v[154:157], v[214:217], v[98:101]
	v_mfma_f32_16x16x32_bf16 v[86:89], v[146:149], v[226:229], v[86:89]
	v_mfma_f32_16x16x32_bf16 v[82:85], v[154:157], v[226:229], v[82:85]
	v_mfma_f32_16x16x32_bf16 v[134:137], v[150:153], v[202:205], v[134:137]
	v_mfma_f32_16x16x32_bf16 v[130:133], v[158:161], v[202:205], v[130:133]
	v_mfma_f32_16x16x32_bf16 v[118:121], v[150:153], v[210:213], v[118:121]
	v_mfma_f32_16x16x32_bf16 v[114:117], v[158:161], v[210:213], v[114:117]
	v_mfma_f32_16x16x32_bf16 v[102:105], v[150:153], v[218:221], v[102:105]
	v_mfma_f32_16x16x32_bf16 v[98:101], v[158:161], v[218:221], v[98:101]
	v_mfma_f32_16x16x32_bf16 v[86:89], v[150:153], v[230:233], v[86:89]
	v_mfma_f32_16x16x32_bf16 v[82:85], v[158:161], v[230:233], v[82:85]
	s_setprio 0
	s_barrier
	s_add_i32 s29, s94, s47
	v_lshl_add_u64 v[186:187], s[6:7], 0, v[166:167]
	s_mov_b32 m0, s29
	ds_read_b128 v[198:201], v194 offset:16384
	ds_read_b128 v[202:205], v194 offset:17408
	ds_read_b128 v[206:209], v194 offset:18432
	ds_read_b128 v[210:213], v194 offset:19456
	ds_read_b128 v[214:217], v194 offset:20480
	ds_read_b128 v[218:221], v194 offset:21504
	ds_read_b128 v[226:229], v194 offset:22528
	ds_read_b128 v[230:233], v194 offset:23552
	global_load_lds_dwordx4 v[186:187], off
	s_add_i32 m0, s29, 0x2000
	s_add_u32 s36, s6, 0x40000
	v_lshl_add_u64 v[222:223], s[6:7], 0, v[170:171]
	s_addc_u32 s37, s7, 0
	s_add_i32 s29, s18, s47
	global_load_lds_dwordx4 v[222:223], off
	v_lshl_add_u64 v[234:235], s[36:37], 0, v[166:167]
	s_mov_b32 m0, s29
	v_lshl_add_u64 v[236:237], s[12:13], 0, v[168:169]
	global_load_lds_dwordx4 v[234:235], off
	v_lshl_add_u64 v[234:235], s[36:37], 0, v[170:171]
	s_add_i32 m0, s29, 0x2000
	s_nop 0
	global_load_lds_dwordx4 v[234:235], off
	v_lshl_add_u64 v[234:235], s[12:13], 0, v[164:165]
	s_mov_b32 m0, s95
	s_nop 0
	global_load_lds_dwordx4 v[234:235], off
	s_mov_b32 m0, s96
	s_nop 0
	global_load_lds_dwordx4 v[236:237], off
	s_waitcnt vmcnt(24)
	s_waitcnt lgkmcnt(0)
	s_barrier
	s_setprio 1
	s_waitcnt lgkmcnt(0)
	v_mfma_f32_16x16x32_bf16 v[78:81], v[26:29], v[198:201], v[78:81]
	v_mfma_f32_16x16x32_bf16 v[74:77], v[42:45], v[198:201], v[74:77]
	v_mfma_f32_16x16x32_bf16 v[62:65], v[26:29], v[206:209], v[62:65]
	v_mfma_f32_16x16x32_bf16 v[58:61], v[42:45], v[206:209], v[58:61]
	v_mfma_f32_16x16x32_bf16 v[38:41], v[26:29], v[214:217], v[38:41]
	v_mfma_f32_16x16x32_bf16 v[34:37], v[42:45], v[214:217], v[34:37]
	v_mfma_f32_16x16x32_bf16 v[14:17], v[26:29], v[226:229], v[14:17]
	v_mfma_f32_16x16x32_bf16 v[10:13], v[42:45], v[226:229], v[10:13]
	v_mfma_f32_16x16x32_bf16 v[78:81], v[30:33], v[202:205], v[78:81]
	v_mfma_f32_16x16x32_bf16 v[74:77], v[46:49], v[202:205], v[74:77]
	v_mfma_f32_16x16x32_bf16 v[62:65], v[30:33], v[210:213], v[62:65]
	v_mfma_f32_16x16x32_bf16 v[58:61], v[46:49], v[210:213], v[58:61]
	v_mfma_f32_16x16x32_bf16 v[38:41], v[30:33], v[218:221], v[38:41]
	v_mfma_f32_16x16x32_bf16 v[34:37], v[46:49], v[218:221], v[34:37]
	v_mfma_f32_16x16x32_bf16 v[14:17], v[30:33], v[230:233], v[14:17]
	v_mfma_f32_16x16x32_bf16 v[10:13], v[46:49], v[230:233], v[10:13]
	s_setprio 0
	s_setprio 1
	v_mfma_f32_16x16x32_bf16 v[22:25], v[146:149], v[214:217], v[22:25]
	v_mfma_f32_16x16x32_bf16 v[18:21], v[154:157], v[214:217], v[18:21]
	v_mfma_f32_16x16x32_bf16 v[6:9], v[146:149], v[226:229], v[6:9]
	v_mfma_f32_16x16x32_bf16 v[2:5], v[154:157], v[226:229], v[2:5]
	v_mfma_f32_16x16x32_bf16 v[26:29], v[146:149], v[198:201], v[70:73]
	v_mfma_f32_16x16x32_bf16 v[30:33], v[154:157], v[198:201], v[66:69]
	v_mfma_f32_16x16x32_bf16 v[42:45], v[146:149], v[206:209], v[54:57]
	v_mfma_f32_16x16x32_bf16 v[46:49], v[154:157], v[206:209], v[50:53]
	v_mfma_f32_16x16x32_bf16 v[22:25], v[150:153], v[218:221], v[22:25]
	v_mfma_f32_16x16x32_bf16 v[18:21], v[158:161], v[218:221], v[18:21]
	v_mfma_f32_16x16x32_bf16 v[6:9], v[150:153], v[230:233], v[6:9]
	v_mfma_f32_16x16x32_bf16 v[2:5], v[158:161], v[230:233], v[2:5]
	v_mfma_f32_16x16x32_bf16 v[26:29], v[150:153], v[202:205], v[26:29]
	v_mfma_f32_16x16x32_bf16 v[30:33], v[158:161], v[202:205], v[30:33]
	v_mfma_f32_16x16x32_bf16 v[42:45], v[150:153], v[210:213], v[42:45]
	v_mfma_f32_16x16x32_bf16 v[46:49], v[158:161], v[210:213], v[46:49]
	s_setprio 0
	s_barrier
	s_branch .Lmid_P1
; #define PG8_STAGE(bufoff, gbase, voff) do { _Pragma("unroll") for (int _i = 0; _i < 2; ++_i) \
;         __builtin_amdgcn_global_load_lds((const unsigned*)((const char*)(gbase) + (voff)[_i]), (LAS unsigned*)(lds + (bufoff) + ldsw + _i * 8192), 16, 0, 0); } while (0)
; #define PG8_LDA(dst, b, h) do { _Pragma("unroll") for (int m = 0; m < 4; ++m) _Pragma("unroll") for (int k = 0; k < 2; ++k) dst[m][k] = *(const LAS bf16x8*)(lds + PG8_SA(b, h) + aoff + m * 2048 + k * 1024); } while (0)
; #define PG8_LDB(dst, b, h) do { _Pragma("unroll") for (int n = 0; n < 2; ++n) _Pragma("unroll") for (int k = 0; k < 2; ++k) dst[n][k] = *(const LAS bf16x8*)(lds + PG8_SB(b, h) + boff + n * 2048 + k * 1024); } while (0)
; #define PG8_MMA(ai, bj, At, Bt) do { __builtin_amdgcn_s_setprio(1); _Pragma("unroll") for (int m = 0; m < 4; ++m) _Pragma("unroll") for (int n = 0; n < 2; ++n) _Pragma("unroll") for (int k = 0; k < 2; ++k) \
;         acc[ai][bj][m][n] = __builtin_amdgcn_mfma_f32_16x16x32_bf16(Bt[n][k], At[m][k], acc[ai][bj][m][n], 0, 0, 0); __builtin_amdgcn_s_setprio(0); } while (0)
; #define PG8_WAIT_V(n) asm volatile("s_waitcnt vmcnt(" #n ")" ::: "memory")
; #define PG8_WAIT_L(n) asm volatile("s_waitcnt lgkmcnt(" #n ")" ::: "memory")
; #define PG8_BAR __builtin_amdgcn_s_barrier()
; template <class Epi, int AC0, int BC0, int NT0, int AC1, int BC1, int NT1>
; __device__ __forceinline__ void gemm_phase(LAS unsigned char* lds, const Gemm g, const StaticOrder& S, const Epi& E, int tid) {
;     ...
;         for (int t = 0; t < nt; t += 2) {
;             const bool last = (t == nt - 2);
;             const char* a1 = cA + (size_t)(t + 1) * kstep;
;             const char* a2 = last ? nA : cA + (size_t)(t + 2) * kstep; const char* b2 = last ? nB : cB + (size_t)(t + 2) * kstep;
;             const char* a3 = a2 + kstep; const char* b3 = b2 + kstep;
;             PG8_LDB(B0, 0, 0); PG8_LDB(B1, 0, 1); PG8_SCHED; PG8_LDA(At, 0, 0); PG8_STAGE(PG8_SA(1, 1), a1 + hstepA, voffA);
;             PG8_WAIT_V(8); PG8_WAIT_L(0); PG8_BAR; PG8_MMA(0, 0, At, B0); PG8_MMA(0, 1, At, B1); PG8_BAR; PG8_SCHED;
;             PG8_LDA(At, 0, 1); PG8_STAGE(PG8_SB(0, 0), b2, voffB); PG8_STAGE(PG8_SB(0, 1), b2 + hstepB, voffB); PG8_STAGE(PG8_SA(0, 0), a2, voffA);
;             PG8_WAIT_V(8); PG8_WAIT_L(0); PG8_BAR; PG8_MMA(1, 0, At, B0); PG8_MMA(1, 1, At, B1); PG8_BAR; PG8_SCHED;
.LBB0_124:
	ds_read_b128 v[26:29], v192
	ds_read_b128 v[30:33], v192 offset:1024
	ds_read_b128 v[42:45], v192 offset:2048
	ds_read_b128 v[46:49], v192 offset:3072
	ds_read_b128 v[146:149], v193
	ds_read_b128 v[150:153], v193 offset:1024
	ds_read_b128 v[154:157], v193 offset:2048
	ds_read_b128 v[158:161], v193 offset:3072
	s_add_u32 s6, s0, 0xfffc0080
	s_addc_u32 s7, s1, -1
	s_cmp_eq_u32 s27, 12
	s_cselect_b32 s13, s3, s7
	s_cselect_b32 s12, s9, s6
	s_cselect_b32 s7, s11, s22
	s_cselect_b32 s6, s15, s16
	v_lshl_add_u64 v[186:187], s[0:1], 0, v[178:179]
	s_add_i32 m0, s95, 0xc000
	ds_read_b128 v[198:201], v194
	ds_read_b128 v[202:205], v194 offset:1024
	ds_read_b128 v[206:209], v194 offset:2048
	ds_read_b128 v[210:213], v194 offset:3072
	ds_read_b128 v[214:217], v194 offset:4096
	ds_read_b128 v[218:221], v194 offset:5120
	ds_read_b128 v[226:229], v194 offset:6144
	ds_read_b128 v[230:233], v194 offset:7168
	global_load_lds_dwordx4 v[186:187], off
	v_lshl_add_u64 v[186:187], s[0:1], 0, v[180:181]
	s_add_i32 m0, s95, 0xe000
	s_nop 0
	global_load_lds_dwordx4 v[186:187], off
	s_waitcnt vmcnt(8)
	s_waitcnt lgkmcnt(0)
	s_barrier
	s_setprio 1
	s_waitcnt lgkmcnt(0)
	v_mfma_f32_16x16x32_bf16 v[142:145], v[26:29], v[198:201], v[142:145]
	v_mfma_f32_16x16x32_bf16 v[138:141], v[42:45], v[198:201], v[138:141]
	v_mfma_f32_16x16x32_bf16 v[126:129], v[26:29], v[206:209], v[126:129]
	v_mfma_f32_16x16x32_bf16 v[122:125], v[42:45], v[206:209], v[122:125]
	v_mfma_f32_16x16x32_bf16 v[110:113], v[26:29], v[214:217], v[110:113]
	v_mfma_f32_16x16x32_bf16 v[106:109], v[42:45], v[214:217], v[106:109]
	v_mfma_f32_16x16x32_bf16 v[94:97], v[26:29], v[226:229], v[94:97]
	v_mfma_f32_16x16x32_bf16 v[90:93], v[42:45], v[226:229], v[90:93]
	v_mfma_f32_16x16x32_bf16 v[142:145], v[30:33], v[202:205], v[142:145]
	v_mfma_f32_16x16x32_bf16 v[138:141], v[46:49], v[202:205], v[138:141]
	v_mfma_f32_16x16x32_bf16 v[126:129], v[30:33], v[210:213], v[126:129]
	v_mfma_f32_16x16x32_bf16 v[122:125], v[46:49], v[210:213], v[122:125]
	v_mfma_f32_16x16x32_bf16 v[110:113], v[30:33], v[218:221], v[110:113]
	v_mfma_f32_16x16x32_bf16 v[106:109], v[46:49], v[218:221], v[106:109]
	v_mfma_f32_16x16x32_bf16 v[94:97], v[30:33], v[230:233], v[94:97]
	v_mfma_f32_16x16x32_bf16 v[90:93], v[46:49], v[230:233], v[90:93]
	s_setprio 0
	s_setprio 1
	v_mfma_f32_16x16x32_bf16 v[134:137], v[146:149], v[198:201], v[134:137]
	v_mfma_f32_16x16x32_bf16 v[130:133], v[154:157], v[198:201], v[130:133]
	v_mfma_f32_16x16x32_bf16 v[118:121], v[146:149], v[206:209], v[118:121]
	v_mfma_f32_16x16x32_bf16 v[114:117], v[154:157], v[206:209], v[114:117]
	v_mfma_f32_16x16x32_bf16 v[102:105], v[146:149], v[214:217], v[102:105]
	v_mfma_f32_16x16x32_bf16 v[98:101], v[154:157], v[214:217], v[98:101]
	v_mfma_f32_16x16x32_bf16 v[86:89], v[146:149], v[226:229], v[86:89]
	v_mfma_f32_16x16x32_bf16 v[82:85], v[154:157], v[226:229], v[82:85]
	v_mfma_f32_16x16x32_bf16 v[134:137], v[150:153], v[202:205], v[134:137]
	v_mfma_f32_16x16x32_bf16 v[130:133], v[158:161], v[202:205], v[130:133]
	v_mfma_f32_16x16x32_bf16 v[118:121], v[150:153], v[210:213], v[118:121]
	v_mfma_f32_16x16x32_bf16 v[114:117], v[158:161], v[210:213], v[114:117]
	v_mfma_f32_16x16x32_bf16 v[102:105], v[150:153], v[218:221], v[102:105]
	v_mfma_f32_16x16x32_bf16 v[98:101], v[158:161], v[218:221], v[98:101]
	v_mfma_f32_16x16x32_bf16 v[86:89], v[150:153], v[230:233], v[86:89]
	v_mfma_f32_16x16x32_bf16 v[82:85], v[158:161], v[230:233], v[82:85]
	s_setprio 0
	s_barrier
	s_add_i32 s29, s94, s47
	v_lshl_add_u64 v[186:187], s[6:7], 0, v[166:167]
	s_mov_b32 m0, s29
	ds_read_b128 v[198:201], v194 offset:16384
	ds_read_b128 v[202:205], v194 offset:17408
	ds_read_b128 v[206:209], v194 offset:18432
	ds_read_b128 v[210:213], v194 offset:19456
	ds_read_b128 v[214:217], v194 offset:20480
	ds_read_b128 v[218:221], v194 offset:21504
	ds_read_b128 v[226:229], v194 offset:22528
	ds_read_b128 v[230:233], v194 offset:23552
	global_load_lds_dwordx4 v[186:187], off
	s_add_i32 m0, s29, 0x2000
	s_add_u32 s36, s6, 0x40000
	v_lshl_add_u64 v[222:223], s[6:7], 0, v[170:171]
	s_addc_u32 s37, s7, 0
	s_add_i32 s29, s18, s47
	global_load_lds_dwordx4 v[222:223], off
	v_lshl_add_u64 v[234:235], s[36:37], 0, v[166:167]
	s_mov_b32 m0, s29
	v_lshl_add_u64 v[236:237], s[12:13], 0, v[168:169]
	global_load_lds_dwordx4 v[234:235], off
	v_lshl_add_u64 v[234:235], s[36:37], 0, v[170:171]
	s_add_i32 m0, s29, 0x2000
	s_nop 0
	global_load_lds_dwordx4 v[234:235], off
	v_lshl_add_u64 v[234:235], s[12:13], 0, v[164:165]
	s_mov_b32 m0, s95
	s_nop 0
	global_load_lds_dwordx4 v[234:235], off
	s_mov_b32 m0, s96
	s_nop 0
	global_load_lds_dwordx4 v[236:237], off
	s_waitcnt vmcnt(8)
	s_waitcnt lgkmcnt(0)
	s_barrier
	s_setprio 1
	s_waitcnt lgkmcnt(0)
	v_mfma_f32_16x16x32_bf16 v[78:81], v[26:29], v[198:201], v[78:81]
	v_mfma_f32_16x16x32_bf16 v[74:77], v[42:45], v[198:201], v[74:77]
	v_mfma_f32_16x16x32_bf16 v[62:65], v[26:29], v[206:209], v[62:65]
	v_mfma_f32_16x16x32_bf16 v[58:61], v[42:45], v[206:209], v[58:61]
	v_mfma_f32_16x16x32_bf16 v[38:41], v[26:29], v[214:217], v[38:41]
	v_mfma_f32_16x16x32_bf16 v[34:37], v[42:45], v[214:217], v[34:37]
	v_mfma_f32_16x16x32_bf16 v[14:17], v[26:29], v[226:229], v[14:17]
	v_mfma_f32_16x16x32_bf16 v[10:13], v[42:45], v[226:229], v[10:13]
	v_mfma_f32_16x16x32_bf16 v[78:81], v[30:33], v[202:205], v[78:81]
	v_mfma_f32_16x16x32_bf16 v[74:77], v[46:49], v[202:205], v[74:77]
	v_mfma_f32_16x16x32_bf16 v[62:65], v[30:33], v[210:213], v[62:65]
	v_mfma_f32_16x16x32_bf16 v[58:61], v[46:49], v[210:213], v[58:61]
	v_mfma_f32_16x16x32_bf16 v[38:41], v[30:33], v[218:221], v[38:41]
	v_mfma_f32_16x16x32_bf16 v[34:37], v[46:49], v[218:221], v[34:37]
	v_mfma_f32_16x16x32_bf16 v[14:17], v[30:33], v[230:233], v[14:17]
	v_mfma_f32_16x16x32_bf16 v[10:13], v[46:49], v[230:233], v[10:13]
	s_setprio 0
	s_setprio 1
	v_mfma_f32_16x16x32_bf16 v[22:25], v[146:149], v[214:217], v[22:25]
	v_mfma_f32_16x16x32_bf16 v[18:21], v[154:157], v[214:217], v[18:21]
	v_mfma_f32_16x16x32_bf16 v[6:9], v[146:149], v[226:229], v[6:9]
	v_mfma_f32_16x16x32_bf16 v[2:5], v[154:157], v[226:229], v[2:5]
	v_mfma_f32_16x16x32_bf16 v[26:29], v[146:149], v[198:201], v[70:73]
	v_mfma_f32_16x16x32_bf16 v[30:33], v[154:157], v[198:201], v[66:69]
	v_mfma_f32_16x16x32_bf16 v[42:45], v[146:149], v[206:209], v[54:57]
	v_mfma_f32_16x16x32_bf16 v[46:49], v[154:157], v[206:209], v[50:53]
	v_mfma_f32_16x16x32_bf16 v[22:25], v[150:153], v[218:221], v[22:25]
	v_mfma_f32_16x16x32_bf16 v[18:21], v[158:161], v[218:221], v[18:21]
	v_mfma_f32_16x16x32_bf16 v[6:9], v[150:153], v[230:233], v[6:9]
	v_mfma_f32_16x16x32_bf16 v[2:5], v[158:161], v[230:233], v[2:5]
	v_mfma_f32_16x16x32_bf16 v[26:29], v[150:153], v[202:205], v[26:29]
	v_mfma_f32_16x16x32_bf16 v[30:33], v[158:161], v[202:205], v[30:33]
	v_mfma_f32_16x16x32_bf16 v[42:45], v[150:153], v[210:213], v[42:45]
	v_mfma_f32_16x16x32_bf16 v[46:49], v[158:161], v[210:213], v[46:49]
	s_setprio 0
	s_barrier
; #define PG8_STAGE(bufoff, gbase, voff) do { _Pragma("unroll") for (int _i = 0; _i < 2; ++_i) \
;         __builtin_amdgcn_global_load_lds((const unsigned*)((const char*)(gbase) + (voff)[_i]), (LAS unsigned*)(lds + (bufoff) + ldsw + _i * 8192), 16, 0, 0); } while (0)
; #define PG8_LDA(dst, b, h) do { _Pragma("unroll") for (int m = 0; m < 4; ++m) _Pragma("unroll") for (int k = 0; k < 2; ++k) dst[m][k] = *(const LAS bf16x8*)(lds + PG8_SA(b, h) + aoff + m * 2048 + k * 1024); } while (0)
; #define PG8_LDB(dst, b, h) do { _Pragma("unroll") for (int n = 0; n < 2; ++n) _Pragma("unroll") for (int k = 0; k < 2; ++k) dst[n][k] = *(const LAS bf16x8*)(lds + PG8_SB(b, h) + boff + n * 2048 + k * 1024); } while (0)
; #define PG8_MMA(ai, bj, At, Bt) do { __builtin_amdgcn_s_setprio(1); _Pragma("unroll") for (int m = 0; m < 4; ++m) _Pragma("unroll") for (int n = 0; n < 2; ++n) _Pragma("unroll") for (int k = 0; k < 2; ++k) \
;         acc[ai][bj][m][n] = __builtin_amdgcn_mfma_f32_16x16x32_bf16(Bt[n][k], At[m][k], acc[ai][bj][m][n], 0, 0, 0); __builtin_amdgcn_s_setprio(0); } while (0)
; #define PG8_WAIT_V(n) asm volatile("s_waitcnt vmcnt(" #n ")" ::: "memory")
; #define PG8_WAIT_L(n) asm volatile("s_waitcnt lgkmcnt(" #n ")" ::: "memory")
; #define PG8_BAR __builtin_amdgcn_s_barrier()
; #define PG8_SCHED __builtin_amdgcn_sched_barrier(0)
; template <class Epi, int AC0, int BC0, int NT0, int AC1, int BC1, int NT1>
; __device__ __forceinline__ void gemm_phase(LAS unsigned char* lds, const Gemm g, const StaticOrder& S, const Epi& E, int tid) {
;     ...
;             PG8_LDB(B0, 1, 0); PG8_LDB(B1, 1, 1); PG8_SCHED; PG8_LDA(At, 1, 0); PG8_STAGE(PG8_SA(0, 1), a2 + hstepA, voffA);
;             PG8_WAIT_V(8); PG8_WAIT_L(0); PG8_BAR; PG8_MMA(0, 0, At, B0); PG8_MMA(0, 1, At, B1); PG8_BAR; PG8_SCHED;
.Lmid_P1:
	s_add_i32 s29, 0, 0x18000
	s_add_i32 s33, 0, 0x1c000
	v_add_u32_e32 v70, s29, v188
	v_add_u32_e32 v158, s33, v188
	ds_read_b128 v[50:53], v70
	ds_read_b128 v[54:57], v70 offset:1024
	ds_read_b128 v[66:69], v70 offset:2048
	ds_read_b128 v[70:73], v70 offset:3072
	ds_read_b128 v[146:149], v158
	ds_read_b128 v[150:153], v158 offset:1024
	ds_read_b128 v[154:157], v158 offset:2048
	ds_read_b128 v[158:161], v158 offset:3072
	s_add_u32 s12, s12, 0x40000
	s_addc_u32 s13, s13, 0
	s_mov_b32 m0, s97
	v_lshl_add_u64 v[238:239], s[12:13], 0, v[164:165]
	ds_read_b128 v[198:201], v194 offset:32768
	ds_read_b128 v[202:205], v194 offset:33792
	ds_read_b128 v[206:209], v194 offset:34816
	ds_read_b128 v[210:213], v194 offset:35840
	ds_read_b128 v[214:217], v194 offset:36864
	ds_read_b128 v[218:221], v194 offset:37888
	ds_read_b128 v[226:229], v194 offset:38912
	ds_read_b128 v[230:233], v194 offset:39936
	global_load_lds_dwordx4 v[238:239], off
	v_lshl_add_u64 v[238:239], s[12:13], 0, v[168:169]
	s_mov_b32 m0, s93
	s_nop 0
	global_load_lds_dwordx4 v[238:239], off
	s_waitcnt vmcnt(8)
	s_waitcnt lgkmcnt(0)
	s_barrier
	s_setprio 1
	s_waitcnt lgkmcnt(0)
	v_mfma_f32_16x16x32_bf16 v[142:145], v[50:53], v[198:201], v[142:145]
	v_mfma_f32_16x16x32_bf16 v[138:141], v[66:69], v[198:201], v[138:141]
	v_mfma_f32_16x16x32_bf16 v[126:129], v[50:53], v[206:209], v[126:129]
	v_mfma_f32_16x16x32_bf16 v[122:125], v[66:69], v[206:209], v[122:125]
	v_mfma_f32_16x16x32_bf16 v[110:113], v[50:53], v[214:217], v[110:113]
	v_mfma_f32_16x16x32_bf16 v[106:109], v[66:69], v[214:217], v[106:109]
	v_mfma_f32_16x16x32_bf16 v[94:97], v[50:53], v[226:229], v[94:97]
	v_mfma_f32_16x16x32_bf16 v[90:93], v[66:69], v[226:229], v[90:93]
	v_mfma_f32_16x16x32_bf16 v[142:145], v[54:57], v[202:205], v[142:145]
	v_mfma_f32_16x16x32_bf16 v[138:141], v[70:73], v[202:205], v[138:141]
	v_mfma_f32_16x16x32_bf16 v[126:129], v[54:57], v[210:213], v[126:129]
	v_mfma_f32_16x16x32_bf16 v[122:125], v[70:73], v[210:213], v[122:125]
	v_mfma_f32_16x16x32_bf16 v[110:113], v[54:57], v[218:221], v[110:113]
	v_mfma_f32_16x16x32_bf16 v[106:109], v[70:73], v[218:221], v[106:109]
	v_mfma_f32_16x16x32_bf16 v[94:97], v[54:57], v[230:233], v[94:97]
	v_mfma_f32_16x16x32_bf16 v[90:93], v[70:73], v[230:233], v[90:93]
	s_setprio 0
	s_setprio 1
	v_mfma_f32_16x16x32_bf16 v[134:137], v[146:149], v[198:201], v[134:137]
	v_mfma_f32_16x16x32_bf16 v[130:133], v[154:157], v[198:201], v[130:133]
	v_mfma_f32_16x16x32_bf16 v[118:121], v[146:149], v[206:209], v[118:121]
	v_mfma_f32_16x16x32_bf16 v[114:117], v[154:157], v[206:209], v[114:117]
	v_mfma_f32_16x16x32_bf16 v[102:105], v[146:149], v[214:217], v[102:105]
	v_mfma_f32_16x16x32_bf16 v[98:101], v[154:157], v[214:217], v[98:101]
	v_mfma_f32_16x16x32_bf16 v[86:89], v[146:149], v[226:229], v[86:89]
	v_mfma_f32_16x16x32_bf16 v[82:85], v[154:157], v[226:229], v[82:85]
	v_mfma_f32_16x16x32_bf16 v[134:137], v[150:153], v[202:205], v[134:137]
	v_mfma_f32_16x16x32_bf16 v[130:133], v[158:161], v[202:205], v[130:133]
	v_mfma_f32_16x16x32_bf16 v[118:121], v[150:153], v[210:213], v[118:121]
	v_mfma_f32_16x16x32_bf16 v[114:117], v[158:161], v[210:213], v[114:117]
	v_mfma_f32_16x16x32_bf16 v[102:105], v[150:153], v[218:221], v[102:105]
	v_mfma_f32_16x16x32_bf16 v[98:101], v[158:161], v[218:221], v[98:101]
	v_mfma_f32_16x16x32_bf16 v[86:89], v[150:153], v[230:233], v[86:89]
	v_mfma_f32_16x16x32_bf16 v[82:85], v[158:161], v[230:233], v[82:85]
	s_setprio 0
	s_barrier
; #define PG8_STAGE(bufoff, gbase, voff) do { _Pragma("unroll") for (int _i = 0; _i < 2; ++_i) \
;         __builtin_amdgcn_global_load_lds((const unsigned*)((const char*)(gbase) + (voff)[_i]), (LAS unsigned*)(lds + (bufoff) + ldsw + _i * 8192), 16, 0, 0); } while (0)
; #define PG8_LDA(dst, b, h) do { _Pragma("unroll") for (int m = 0; m < 4; ++m) _Pragma("unroll") for (int k = 0; k < 2; ++k) dst[m][k] = *(const LAS bf16x8*)(lds + PG8_SA(b, h) + aoff + m * 2048 + k * 1024); } while (0)
; #define PG8_MMA(ai, bj, At, Bt) do { __builtin_amdgcn_s_setprio(1); _Pragma("unroll") for (int m = 0; m < 4; ++m) _Pragma("unroll") for (int n = 0; n < 2; ++n) _Pragma("unroll") for (int k = 0; k < 2; ++k) \
;         acc[ai][bj][m][n] = __builtin_amdgcn_mfma_f32_16x16x32_bf16(Bt[n][k], At[m][k], acc[ai][bj][m][n], 0, 0, 0); __builtin_amdgcn_s_setprio(0); } while (0)
; #define PG8_WAIT_V(n) asm volatile("s_waitcnt vmcnt(" #n ")" ::: "memory")
; #define PG8_WAIT_L(n) asm volatile("s_waitcnt lgkmcnt(" #n ")" ::: "memory")
; #define PG8_BAR __builtin_amdgcn_s_barrier()
; #define PG8_SCHED __builtin_amdgcn_sched_barrier(0)
; template <class Epi, int AC0, int BC0, int NT0, int AC1, int BC1, int NT1>
; __device__ __forceinline__ void gemm_phase(LAS unsigned char* lds, const Gemm g, const StaticOrder& S, const Epi& E, int tid) {
;     ...
;             PG8_LDA(At, 1, 1); PG8_STAGE(PG8_SB(1, 0), b3, voffB); PG8_STAGE(PG8_SB(1, 1), b3 + hstepB, voffB); PG8_STAGE(PG8_SA(1, 0), a3, voffA);
;             PG8_WAIT_V(8); PG8_WAIT_L(0); PG8_BAR; PG8_MMA(1, 0, At, B0); PG8_MMA(1, 1, At, B1); PG8_BAR; PG8_SCHED;
;         }
;         if (wr == 0) PG8_BAR;
	s_add_i32 s12, s29, s47
	v_lshl_add_u64 v[186:187], v[186:187], 0, s[20:21]
	s_mov_b32 m0, s12
	ds_read_b128 v[198:201], v194 offset:49152
	ds_read_b128 v[202:205], v194 offset:50176
	ds_read_b128 v[206:209], v194 offset:51200
	ds_read_b128 v[210:213], v194 offset:52224
	ds_read_b128 v[214:217], v194 offset:53248
	ds_read_b128 v[218:221], v194 offset:54272
	ds_read_b128 v[226:229], v194 offset:55296
	ds_read_b128 v[230:233], v194 offset:56320
	global_load_lds_dwordx4 v[186:187], off
	s_add_i32 m0, s12, 0x2000
	s_add_u32 s6, s6, 0x40080
	v_lshl_add_u64 v[186:187], v[222:223], 0, s[20:21]
	s_addc_u32 s7, s7, 0
	s_add_i32 s12, s33, s47
	global_load_lds_dwordx4 v[186:187], off
	v_lshl_add_u64 v[186:187], s[6:7], 0, v[166:167]
	s_mov_b32 m0, s12
	s_nop 0
	global_load_lds_dwordx4 v[186:187], off
	v_lshl_add_u64 v[186:187], s[6:7], 0, v[170:171]
	s_add_i32 m0, s12, 0x2000
	s_nop 0
	global_load_lds_dwordx4 v[186:187], off
	v_lshl_add_u64 v[186:187], v[234:235], 0, s[20:21]
	s_mov_b32 m0, s19
	s_nop 0
	global_load_lds_dwordx4 v[186:187], off
	v_lshl_add_u64 v[186:187], v[236:237], 0, s[20:21]
	s_mov_b32 m0, s46
	s_nop 0
	global_load_lds_dwordx4 v[186:187], off
	s_waitcnt vmcnt(8)
	s_waitcnt lgkmcnt(0)
	s_barrier
	s_setprio 1
	s_waitcnt lgkmcnt(0)
	v_mfma_f32_16x16x32_bf16 v[78:81], v[50:53], v[198:201], v[78:81]
	v_mfma_f32_16x16x32_bf16 v[74:77], v[66:69], v[198:201], v[74:77]
	v_mfma_f32_16x16x32_bf16 v[62:65], v[50:53], v[206:209], v[62:65]
	v_mfma_f32_16x16x32_bf16 v[58:61], v[66:69], v[206:209], v[58:61]
	v_mfma_f32_16x16x32_bf16 v[38:41], v[50:53], v[214:217], v[38:41]
	v_mfma_f32_16x16x32_bf16 v[34:37], v[66:69], v[214:217], v[34:37]
	v_mfma_f32_16x16x32_bf16 v[14:17], v[50:53], v[226:229], v[14:17]
	v_mfma_f32_16x16x32_bf16 v[10:13], v[66:69], v[226:229], v[10:13]
	v_mfma_f32_16x16x32_bf16 v[78:81], v[54:57], v[202:205], v[78:81]
	v_mfma_f32_16x16x32_bf16 v[74:77], v[70:73], v[202:205], v[74:77]
	v_mfma_f32_16x16x32_bf16 v[62:65], v[54:57], v[210:213], v[62:65]
	v_mfma_f32_16x16x32_bf16 v[58:61], v[70:73], v[210:213], v[58:61]
	v_mfma_f32_16x16x32_bf16 v[38:41], v[54:57], v[218:221], v[38:41]
	v_mfma_f32_16x16x32_bf16 v[34:37], v[70:73], v[218:221], v[34:37]
	v_mfma_f32_16x16x32_bf16 v[14:17], v[54:57], v[230:233], v[14:17]
	v_mfma_f32_16x16x32_bf16 v[10:13], v[70:73], v[230:233], v[10:13]
	s_setprio 0
	s_setprio 1
	v_mfma_f32_16x16x32_bf16 v[26:29], v[146:149], v[198:201], v[26:29]
	v_mfma_f32_16x16x32_bf16 v[70:73], v[150:153], v[202:205], v[26:29]
	v_mfma_f32_16x16x32_bf16 v[26:29], v[154:157], v[198:201], v[30:33]
	v_mfma_f32_16x16x32_bf16 v[66:69], v[158:161], v[202:205], v[26:29]
	v_mfma_f32_16x16x32_bf16 v[26:29], v[146:149], v[206:209], v[42:45]
	v_mfma_f32_16x16x32_bf16 v[54:57], v[150:153], v[210:213], v[26:29]
	v_mfma_f32_16x16x32_bf16 v[26:29], v[154:157], v[206:209], v[46:49]
	v_mfma_f32_16x16x32_bf16 v[22:25], v[146:149], v[214:217], v[22:25]
	v_mfma_f32_16x16x32_bf16 v[18:21], v[154:157], v[214:217], v[18:21]
	v_mfma_f32_16x16x32_bf16 v[6:9], v[146:149], v[226:229], v[6:9]
	v_mfma_f32_16x16x32_bf16 v[2:5], v[154:157], v[226:229], v[2:5]
	v_mfma_f32_16x16x32_bf16 v[50:53], v[158:161], v[210:213], v[26:29]
	v_mfma_f32_16x16x32_bf16 v[22:25], v[150:153], v[218:221], v[22:25]
	v_mfma_f32_16x16x32_bf16 v[18:21], v[158:161], v[218:221], v[18:21]
	v_mfma_f32_16x16x32_bf16 v[6:9], v[150:153], v[230:233], v[6:9]
	v_mfma_f32_16x16x32_bf16 v[2:5], v[158:161], v[230:233], v[2:5]
	s_setprio 0
	s_barrier
	s_add_i32 s27, s27, 2
	s_add_u32 s0, s0, 0x100
	s_addc_u32 s1, s1, 0
	s_add_u32 s16, s16, 0x100
	s_addc_u32 s22, s22, 0
	s_cmp_gt_u32 s27, 13
	s_cbranch_scc0 .LBB0_124
	v_readlane_b32 s0, v254, 21
	v_readlane_b32 s1, v254, 22
	s_and_b64 vcc, exec, s[0:1]
	s_cbranch_vccz .LBB0_127
	s_barrier

;     __device__ __forceinline__ void operator()(f32x4 (&acc)[2][2][4][2], const Unit& u, int wr, int wc, int fr, int fq) const {
;     ...
;                 if (is_norm) {
;                     float ss = 0.f;
; #pragma unroll
;                     for (int bj = 0; bj < 2; ++bj)
; #pragma unroll
;                         for (int n = 0; n < 2; ++n) { const f32x4 x = v[bj][n]; ss += (x[0] * x[0] + x[1] * x[1]) + (x[2] * x[2] + x[3] * x[3]); }
;                     ss += __shfl_xor(ss, 16); ss += __shfl_xor(ss, 32);
;                     const float rs = rsqrtf(ss * (1.f / 64.f) + EPS);
; #pragma unroll
;                     for (int bj = 0; bj < 2; ++bj)
; #pragma unroll
;                         for (int n = 0; n < 2; ++n) v[bj][n] = v[bj][n] * rs * gv[bj][n];
.LBB0_183:
	s_and_b64 vcc, exec, s[0:1]
	s_cbranch_vccz .LBB0_185
	v_pk_mul_f32 v[130:131], v[128:129], v[128:129]
	v_pk_mul_f32 v[132:133], v[126:127], v[126:127]
	s_nop 0
	v_pk_mov_b32 v[134:135], v[132:133], v[130:131] op_sel:[1,0]
	v_mov_b32_e32 v133, v131
	v_pk_add_f32 v[130:131], v[134:135], v[132:133]
	v_pk_mul_f32 v[132:133], v[124:125], v[124:125]
	v_pk_mul_f32 v[134:135], v[122:123], v[122:123]
	v_pk_add_f32 v[130:131], v[130:131], v[130:131] op_sel:[0,1] op_sel_hi:[1,0]
	v_pk_mov_b32 v[136:137], v[134:135], v[132:133] op_sel:[1,0]
	v_mov_b32_e32 v135, v133
	v_pk_add_f32 v[132:133], v[136:137], v[134:135]
	v_mul_f32_e32 v134, v114, v114
	v_mul_f32_e32 v135, v115, v115
	v_pk_add_f32 v[132:133], v[132:133], v[132:133] op_sel:[0,1] op_sel_hi:[1,0]
	v_mov_b32_e32 v131, v134
	v_mov_b32_e32 v133, v135
	v_pk_add_f32 v[130:131], v[130:131], v[132:133]
	v_mul_f32_e32 v132, v119, v119
	v_mul_f32_e32 v134, v121, v121
	v_mul_f32_e32 v136, v116, v116
	v_mul_f32_e32 v137, v117, v117
	v_pk_fma_f32 v[132:133], v[118:119], v[118:119], v[132:133] op_sel_hi:[1,1,0]
	v_pk_fma_f32 v[134:135], v[120:121], v[120:121], v[134:135] op_sel_hi:[1,1,0]
	v_mov_b32_e32 v133, v136
	v_mov_b32_e32 v135, v137
	v_pk_add_f32 v[132:133], v[132:133], v[134:135]
	s_nop 0
	v_pk_add_f32 v[130:131], v[130:131], v[132:133]
	v_and_b32_e32 v132, 64, v196
	v_add_f32_e32 v130, v130, v131
	v_xor_b32_e32 v131, 16, v196
	v_add_u32_e32 v132, 64, v132
	v_cmp_lt_i32_e32 vcc, v131, v132
	s_nop 1
	v_cndmask_b32_e32 v131, v196, v131, vcc
	v_lshlrev_b32_e32 v131, 2, v131
	ds_bpermute_b32 v131, v131, v130
	s_waitcnt lgkmcnt(0)
	v_add_f32_e32 v130, v130, v131
	v_xor_b32_e32 v131, 32, v196
	v_cmp_lt_i32_e32 vcc, v131, v132
	s_nop 1
	v_cndmask_b32_e32 v131, v196, v131, vcc
	v_lshlrev_b32_e32 v131, 2, v131
	ds_bpermute_b32 v131, v131, v130
	s_waitcnt lgkmcnt(0)
	v_add_f32_e32 v130, v130, v131
	v_fmamk_f32 v130, v130, 0x3c800000, v195
	v_mul_f32_e32 v131, 0x4b800000, v130
	v_cmp_gt_f32_e32 vcc, s2, v130
	s_nop 1
	v_cndmask_b32_e32 v130, v130, v131, vcc
	v_rsq_f32_e32 v130, v130
	s_nop 0
	v_mul_f32_e32 v131, 0x45800000, v130
	v_cndmask_b32_e32 v142, v130, v131, vcc
	v_pk_mul_f32 v[126:127], v[126:127], v[142:143] op_sel_hi:[1,0]
	v_pk_mul_f32 v[128:129], v[128:129], v[142:143] op_sel_hi:[1,0]
	v_pk_mul_f32 v[122:123], v[122:123], v[142:143] op_sel_hi:[1,0]
	v_pk_mul_f32 v[124:125], v[124:125], v[142:143] op_sel_hi:[1,0]
	v_pk_mul_f32 v[118:119], v[118:119], v[142:143] op_sel_hi:[1,0]
	v_pk_mul_f32 v[120:121], v[120:121], v[142:143] op_sel_hi:[1,0]
	v_pk_mul_f32 v[114:115], v[114:115], v[142:143] op_sel_hi:[1,0]
	v_pk_mul_f32 v[116:117], v[116:117], v[142:143] op_sel_hi:[1,0]
	v_pk_mul_f32 v[132:133], v[32:33], v[128:129]
	v_pk_mul_f32 v[130:131], v[30:31], v[126:127]
	v_pk_mul_f32 v[136:137], v[28:29], v[124:125]
	v_pk_mul_f32 v[134:135], v[26:27], v[122:123]
	v_pk_mul_f32 v[140:141], v[48:49], v[120:121]
	v_pk_mul_f32 v[138:139], v[46:47], v[118:119]
	v_pk_mul_f32 v[144:145], v[44:45], v[116:117]
	v_pk_mul_f32 v[142:143], v[42:43], v[114:115]

;     __device__ __forceinline__ void operator()(f32x4 (&acc)[2][2][4][2], const Unit& u, int wr, int wc, int fr, int fq) const {
;     ...
;                 if (is_norm) {
;                     float ss = 0.f;
; #pragma unroll
;                     for (int bj = 0; bj < 2; ++bj)
; #pragma unroll
;                         for (int n = 0; n < 2; ++n) { const f32x4 x = v[bj][n]; ss += (x[0] * x[0] + x[1] * x[1]) + (x[2] * x[2] + x[3] * x[3]); }
;                     ss += __shfl_xor(ss, 16); ss += __shfl_xor(ss, 32);
;                     const float rs = rsqrtf(ss * (1.f / 64.f) + EPS);
; #pragma unroll
;                     for (int bj = 0; bj < 2; ++bj)
; #pragma unroll
;                         for (int n = 0; n < 2; ++n) v[bj][n] = v[bj][n] * rs * gv[bj][n];
.LBB0_198:
	s_and_b64 vcc, exec, s[0:1]
	s_cbranch_vccz .LBB0_215
	v_pk_mul_f32 v[114:115], v[112:113], v[112:113]
	v_pk_mul_f32 v[116:117], v[110:111], v[110:111]
	s_nop 0
	v_pk_mov_b32 v[118:119], v[116:117], v[114:115] op_sel:[1,0]
	v_mov_b32_e32 v117, v115
	v_pk_add_f32 v[114:115], v[118:119], v[116:117]
	v_pk_mul_f32 v[116:117], v[108:109], v[108:109]
	v_pk_mul_f32 v[118:119], v[106:107], v[106:107]
	v_pk_add_f32 v[114:115], v[114:115], v[114:115] op_sel:[0,1] op_sel_hi:[1,0]
	v_pk_mov_b32 v[120:121], v[118:119], v[116:117] op_sel:[1,0]
	v_mov_b32_e32 v119, v117
	v_pk_add_f32 v[116:117], v[120:121], v[118:119]
	v_mul_f32_e32 v118, v98, v98
	v_mul_f32_e32 v119, v99, v99
	v_pk_add_f32 v[116:117], v[116:117], v[116:117] op_sel:[0,1] op_sel_hi:[1,0]
	v_mov_b32_e32 v115, v118
	v_mov_b32_e32 v117, v119
	v_pk_add_f32 v[114:115], v[114:115], v[116:117]
	v_mul_f32_e32 v116, v103, v103
	v_mul_f32_e32 v118, v105, v105
	v_mul_f32_e32 v120, v100, v100
	v_mul_f32_e32 v121, v101, v101
	v_pk_fma_f32 v[116:117], v[102:103], v[102:103], v[116:117] op_sel_hi:[1,1,0]
	v_pk_fma_f32 v[118:119], v[104:105], v[104:105], v[118:119] op_sel_hi:[1,1,0]
	v_mov_b32_e32 v117, v120
	v_mov_b32_e32 v119, v121
	v_pk_add_f32 v[116:117], v[116:117], v[118:119]
	s_nop 0
	v_pk_add_f32 v[114:115], v[114:115], v[116:117]
	v_and_b32_e32 v116, 64, v196
	v_add_f32_e32 v114, v114, v115
	v_xor_b32_e32 v115, 16, v196
	v_add_u32_e32 v116, 64, v116
	v_cmp_lt_i32_e32 vcc, v115, v116
	s_nop 1
	v_cndmask_b32_e32 v115, v196, v115, vcc
	v_lshlrev_b32_e32 v115, 2, v115
	ds_bpermute_b32 v115, v115, v114
	s_waitcnt lgkmcnt(0)
	v_add_f32_e32 v114, v114, v115
	v_xor_b32_e32 v115, 32, v196
	v_cmp_lt_i32_e32 vcc, v115, v116
	s_nop 1
	v_cndmask_b32_e32 v115, v196, v115, vcc
	v_lshlrev_b32_e32 v115, 2, v115
	ds_bpermute_b32 v115, v115, v114
	s_waitcnt lgkmcnt(0)
	v_add_f32_e32 v114, v114, v115
	v_fmamk_f32 v114, v114, 0x3c800000, v195
	v_mul_f32_e32 v115, 0x4b800000, v114
	v_cmp_gt_f32_e32 vcc, s2, v114
	s_nop 1
	v_cndmask_b32_e32 v114, v114, v115, vcc
	v_rsq_f32_e32 v114, v114
	s_nop 0
	v_mul_f32_e32 v115, 0x45800000, v114
	v_cndmask_b32_e32 v126, v114, v115, vcc
	v_pk_mul_f32 v[110:111], v[110:111], v[126:127] op_sel_hi:[1,0]
	v_pk_mul_f32 v[112:113], v[112:113], v[126:127] op_sel_hi:[1,0]
	v_pk_mul_f32 v[106:107], v[106:107], v[126:127] op_sel_hi:[1,0]
	v_pk_mul_f32 v[108:109], v[108:109], v[126:127] op_sel_hi:[1,0]
	v_pk_mul_f32 v[102:103], v[102:103], v[126:127] op_sel_hi:[1,0]
	v_pk_mul_f32 v[104:105], v[104:105], v[126:127] op_sel_hi:[1,0]
	v_pk_mul_f32 v[98:99], v[98:99], v[126:127] op_sel_hi:[1,0]
	v_pk_mul_f32 v[100:101], v[100:101], v[126:127] op_sel_hi:[1,0]
	v_pk_mul_f32 v[116:117], v[32:33], v[112:113]
	v_pk_mul_f32 v[114:115], v[30:31], v[110:111]
	v_pk_mul_f32 v[120:121], v[28:29], v[108:109]
	v_pk_mul_f32 v[118:119], v[26:27], v[106:107]
	v_pk_mul_f32 v[124:125], v[48:49], v[104:105]
	v_pk_mul_f32 v[122:123], v[46:47], v[102:103]
	v_pk_mul_f32 v[128:129], v[44:45], v[100:101]
	v_pk_mul_f32 v[126:127], v[42:43], v[98:99]
	s_and_b64 vcc, exec, s[8:9]
	v_or_b32_e32 v100, s27, v190
	s_cbranch_vccnz .LBB0_225
	s_branch .LBB0_216

;     __device__ __forceinline__ void operator()(f32x4 (&acc)[2][2][4][2], const Unit& u, int wr, int wc, int fr, int fq) const {
;     ...
;                 if (is_norm) {
;                     float ss = 0.f;
; #pragma unroll
;                     for (int bj = 0; bj < 2; ++bj)
; #pragma unroll
;                         for (int n = 0; n < 2; ++n) { const f32x4 x = v[bj][n]; ss += (x[0] * x[0] + x[1] * x[1]) + (x[2] * x[2] + x[3] * x[3]); }
;                     ss += __shfl_xor(ss, 16); ss += __shfl_xor(ss, 32);
;                     const float rs = rsqrtf(ss * (1.f / 64.f) + EPS);
; #pragma unroll
;                     for (int bj = 0; bj < 2; ++bj)
; #pragma unroll
;                         for (int n = 0; n < 2; ++n) v[bj][n] = v[bj][n] * rs * gv[bj][n];
.LBB0_228:
	s_and_b64 vcc, exec, s[0:1]
	s_cbranch_vccz .LBB0_245
	v_pk_mul_f32 v[98:99], v[96:97], v[96:97]
	v_pk_mul_f32 v[100:101], v[94:95], v[94:95]
	s_nop 0
	v_pk_mov_b32 v[102:103], v[100:101], v[98:99] op_sel:[1,0]
	v_mov_b32_e32 v101, v99
	v_pk_add_f32 v[98:99], v[102:103], v[100:101]
	v_pk_mul_f32 v[100:101], v[92:93], v[92:93]
	v_pk_mul_f32 v[102:103], v[90:91], v[90:91]
	v_pk_add_f32 v[98:99], v[98:99], v[98:99] op_sel:[0,1] op_sel_hi:[1,0]
	v_pk_mov_b32 v[104:105], v[102:103], v[100:101] op_sel:[1,0]
	v_mov_b32_e32 v103, v101
	v_pk_add_f32 v[100:101], v[104:105], v[102:103]
	v_mul_f32_e32 v102, v82, v82
	v_mul_f32_e32 v103, v83, v83
	v_pk_add_f32 v[100:101], v[100:101], v[100:101] op_sel:[0,1] op_sel_hi:[1,0]
	v_mov_b32_e32 v99, v102
	v_mov_b32_e32 v101, v103
	v_pk_add_f32 v[98:99], v[98:99], v[100:101]
	v_mul_f32_e32 v100, v87, v87
	v_mul_f32_e32 v102, v89, v89
	v_mul_f32_e32 v104, v84, v84
	v_mul_f32_e32 v105, v85, v85
	v_pk_fma_f32 v[100:101], v[86:87], v[86:87], v[100:101] op_sel_hi:[1,1,0]
	v_pk_fma_f32 v[102:103], v[88:89], v[88:89], v[102:103] op_sel_hi:[1,1,0]
	v_mov_b32_e32 v101, v104
	v_mov_b32_e32 v103, v105
	v_pk_add_f32 v[100:101], v[100:101], v[102:103]
	s_nop 0
	v_pk_add_f32 v[98:99], v[98:99], v[100:101]
	v_and_b32_e32 v100, 64, v196
	v_add_f32_e32 v98, v98, v99
	v_xor_b32_e32 v99, 16, v196
	v_add_u32_e32 v100, 64, v100
	v_cmp_lt_i32_e32 vcc, v99, v100
	s_nop 1
	v_cndmask_b32_e32 v99, v196, v99, vcc
	v_lshlrev_b32_e32 v99, 2, v99
	ds_bpermute_b32 v99, v99, v98
	s_waitcnt lgkmcnt(0)
	v_add_f32_e32 v98, v98, v99
	v_xor_b32_e32 v99, 32, v196
	v_cmp_lt_i32_e32 vcc, v99, v100
	s_nop 1
	v_cndmask_b32_e32 v99, v196, v99, vcc
	v_lshlrev_b32_e32 v99, 2, v99
	ds_bpermute_b32 v99, v99, v98
	s_waitcnt lgkmcnt(0)
	v_add_f32_e32 v98, v98, v99
	v_fmamk_f32 v98, v98, 0x3c800000, v195
	v_mul_f32_e32 v99, 0x4b800000, v98
	v_cmp_gt_f32_e32 vcc, s2, v98
	s_nop 1
	v_cndmask_b32_e32 v98, v98, v99, vcc
	v_rsq_f32_e32 v98, v98
	s_nop 0
	v_mul_f32_e32 v99, 0x45800000, v98
	v_cndmask_b32_e32 v110, v98, v99, vcc
	v_pk_mul_f32 v[94:95], v[94:95], v[110:111] op_sel_hi:[1,0]
	v_pk_mul_f32 v[96:97], v[96:97], v[110:111] op_sel_hi:[1,0]
	v_pk_mul_f32 v[90:91], v[90:91], v[110:111] op_sel_hi:[1,0]
	v_pk_mul_f32 v[92:93], v[92:93], v[110:111] op_sel_hi:[1,0]
	v_pk_mul_f32 v[86:87], v[86:87], v[110:111] op_sel_hi:[1,0]
	v_pk_mul_f32 v[88:89], v[88:89], v[110:111] op_sel_hi:[1,0]
	v_pk_mul_f32 v[82:83], v[82:83], v[110:111] op_sel_hi:[1,0]
	v_pk_mul_f32 v[84:85], v[84:85], v[110:111] op_sel_hi:[1,0]
	v_pk_mul_f32 v[100:101], v[32:33], v[96:97]
	v_pk_mul_f32 v[98:99], v[30:31], v[94:95]
	v_pk_mul_f32 v[104:105], v[28:29], v[92:93]
	v_pk_mul_f32 v[102:103], v[26:27], v[90:91]
	v_pk_mul_f32 v[108:109], v[48:49], v[88:89]
	v_pk_mul_f32 v[106:107], v[46:47], v[86:87]
	v_pk_mul_f32 v[112:113], v[44:45], v[84:85]
	v_pk_mul_f32 v[110:111], v[42:43], v[82:83]
	s_and_b64 vcc, exec, s[8:9]
	v_or_b32_e32 v84, s27, v191
	s_cbranch_vccnz .LBB0_255
	s_branch .LBB0_246

;     __device__ __forceinline__ void operator()(f32x4 (&acc)[2][2][4][2], const Unit& u, int wr, int wc, int fr, int fq) const {
;     ...
;                 if (is_norm) {
;                     float ss = 0.f;
; #pragma unroll
;                     for (int bj = 0; bj < 2; ++bj)
; #pragma unroll
;                         for (int n = 0; n < 2; ++n) { const f32x4 x = v[bj][n]; ss += (x[0] * x[0] + x[1] * x[1]) + (x[2] * x[2] + x[3] * x[3]); }
;                     ss += __shfl_xor(ss, 16); ss += __shfl_xor(ss, 32);
;                     const float rs = rsqrtf(ss * (1.f / 64.f) + EPS);
; #pragma unroll
;                     for (int bj = 0; bj < 2; ++bj)
; #pragma unroll
;                         for (int n = 0; n < 2; ++n) v[bj][n] = v[bj][n] * rs * gv[bj][n];
.LBB0_273:
	s_and_b64 vcc, exec, s[0:1]
	s_cbranch_vccz .LBB0_275
	v_pk_mul_f32 v[82:83], v[80:81], v[80:81]
	v_pk_mul_f32 v[84:85], v[78:79], v[78:79]
	s_nop 0
	v_pk_mov_b32 v[86:87], v[84:85], v[82:83] op_sel:[1,0]
	v_mov_b32_e32 v85, v83
	v_pk_add_f32 v[82:83], v[86:87], v[84:85]
	v_pk_mul_f32 v[84:85], v[76:77], v[76:77]
	v_pk_mul_f32 v[86:87], v[74:75], v[74:75]
	v_pk_add_f32 v[82:83], v[82:83], v[82:83] op_sel:[0,1] op_sel_hi:[1,0]
	v_pk_mov_b32 v[88:89], v[86:87], v[84:85] op_sel:[1,0]
	v_mov_b32_e32 v87, v85
	v_pk_add_f32 v[84:85], v[88:89], v[86:87]
	v_mul_f32_e32 v86, v66, v66
	v_mul_f32_e32 v87, v67, v67
	v_pk_add_f32 v[84:85], v[84:85], v[84:85] op_sel:[0,1] op_sel_hi:[1,0]
	v_mov_b32_e32 v83, v86
	v_mov_b32_e32 v85, v87
	v_pk_add_f32 v[82:83], v[82:83], v[84:85]
	v_mul_f32_e32 v84, v71, v71
	v_mul_f32_e32 v86, v73, v73
	v_mul_f32_e32 v88, v68, v68
	v_mul_f32_e32 v89, v69, v69
	v_pk_fma_f32 v[84:85], v[70:71], v[70:71], v[84:85] op_sel_hi:[1,1,0]
	v_pk_fma_f32 v[86:87], v[72:73], v[72:73], v[86:87] op_sel_hi:[1,1,0]
	v_mov_b32_e32 v85, v88
	v_mov_b32_e32 v87, v89
	v_pk_add_f32 v[84:85], v[84:85], v[86:87]
	s_nop 0
	v_pk_add_f32 v[82:83], v[82:83], v[84:85]
	v_and_b32_e32 v84, 64, v196
	v_add_f32_e32 v82, v82, v83
	v_xor_b32_e32 v83, 16, v196
	v_add_u32_e32 v84, 64, v84
	v_cmp_lt_i32_e32 vcc, v83, v84
	s_nop 1
	v_cndmask_b32_e32 v83, v196, v83, vcc
	v_lshlrev_b32_e32 v83, 2, v83
	ds_bpermute_b32 v83, v83, v82
	s_waitcnt lgkmcnt(0)
	v_add_f32_e32 v82, v82, v83
	v_xor_b32_e32 v83, 32, v196
	v_cmp_lt_i32_e32 vcc, v83, v84
	s_nop 1
	v_cndmask_b32_e32 v83, v196, v83, vcc
	v_lshlrev_b32_e32 v83, 2, v83
	ds_bpermute_b32 v83, v83, v82
	s_waitcnt lgkmcnt(0)
	v_add_f32_e32 v82, v82, v83
	v_fmamk_f32 v82, v82, 0x3c800000, v195
	v_mul_f32_e32 v83, 0x4b800000, v82
	v_cmp_gt_f32_e32 vcc, s2, v82
	s_nop 1
	v_cndmask_b32_e32 v82, v82, v83, vcc
	v_rsq_f32_e32 v82, v82
	s_nop 0
	v_mul_f32_e32 v83, 0x45800000, v82
	v_cndmask_b32_e32 v94, v82, v83, vcc
	v_pk_mul_f32 v[78:79], v[78:79], v[94:95] op_sel_hi:[1,0]
	v_pk_mul_f32 v[80:81], v[80:81], v[94:95] op_sel_hi:[1,0]
	v_pk_mul_f32 v[74:75], v[74:75], v[94:95] op_sel_hi:[1,0]
	v_pk_mul_f32 v[76:77], v[76:77], v[94:95] op_sel_hi:[1,0]
	v_pk_mul_f32 v[70:71], v[70:71], v[94:95] op_sel_hi:[1,0]
	v_pk_mul_f32 v[72:73], v[72:73], v[94:95] op_sel_hi:[1,0]
	v_pk_mul_f32 v[66:67], v[66:67], v[94:95] op_sel_hi:[1,0]
	v_pk_mul_f32 v[68:69], v[68:69], v[94:95] op_sel_hi:[1,0]
	v_pk_mul_f32 v[84:85], v[32:33], v[80:81]
	v_pk_mul_f32 v[82:83], v[30:31], v[78:79]
	v_pk_mul_f32 v[88:89], v[28:29], v[76:77]
	v_pk_mul_f32 v[86:87], v[26:27], v[74:75]
	v_pk_mul_f32 v[92:93], v[48:49], v[72:73]
	v_pk_mul_f32 v[90:91], v[46:47], v[70:71]
	v_pk_mul_f32 v[96:97], v[44:45], v[68:69]
	v_pk_mul_f32 v[94:95], v[42:43], v[66:67]

;     __device__ __forceinline__ void operator()(f32x4 (&acc)[2][2][4][2], const Unit& u, int wr, int wc, int fr, int fq) const {
;     ...
;                 if (is_norm) {
;                     float ss = 0.f;
; #pragma unroll
;                     for (int bj = 0; bj < 2; ++bj)
; #pragma unroll
;                         for (int n = 0; n < 2; ++n) { const f32x4 x = v[bj][n]; ss += (x[0] * x[0] + x[1] * x[1]) + (x[2] * x[2] + x[3] * x[3]); }
;                     ss += __shfl_xor(ss, 16); ss += __shfl_xor(ss, 32);
;                     const float rs = rsqrtf(ss * (1.f / 64.f) + EPS);
; #pragma unroll
;                     for (int bj = 0; bj < 2; ++bj)
; #pragma unroll
;                         for (int n = 0; n < 2; ++n) v[bj][n] = v[bj][n] * rs * gv[bj][n];
.LBB0_288:
	s_and_b64 vcc, exec, s[0:1]
	s_cbranch_vccz .LBB0_305
	v_pk_mul_f32 v[66:67], v[64:65], v[64:65]
	v_pk_mul_f32 v[68:69], v[62:63], v[62:63]
	s_nop 0
	v_pk_mov_b32 v[70:71], v[68:69], v[66:67] op_sel:[1,0]
	v_mov_b32_e32 v69, v67
	v_pk_add_f32 v[66:67], v[70:71], v[68:69]
	v_pk_mul_f32 v[68:69], v[60:61], v[60:61]
	v_pk_mul_f32 v[70:71], v[58:59], v[58:59]
	v_pk_add_f32 v[66:67], v[66:67], v[66:67] op_sel:[0,1] op_sel_hi:[1,0]
	v_pk_mov_b32 v[72:73], v[70:71], v[68:69] op_sel:[1,0]
	v_mov_b32_e32 v71, v69
	v_pk_add_f32 v[68:69], v[72:73], v[70:71]
	v_mul_f32_e32 v70, v50, v50
	v_mul_f32_e32 v71, v51, v51
	v_pk_add_f32 v[68:69], v[68:69], v[68:69] op_sel:[0,1] op_sel_hi:[1,0]
	v_mov_b32_e32 v67, v70
	v_mov_b32_e32 v69, v71
	v_pk_add_f32 v[66:67], v[66:67], v[68:69]
	v_mul_f32_e32 v68, v55, v55
	v_mul_f32_e32 v70, v57, v57
	v_mul_f32_e32 v72, v52, v52
	v_mul_f32_e32 v73, v53, v53
	v_pk_fma_f32 v[68:69], v[54:55], v[54:55], v[68:69] op_sel_hi:[1,1,0]
	v_pk_fma_f32 v[70:71], v[56:57], v[56:57], v[70:71] op_sel_hi:[1,1,0]
	v_mov_b32_e32 v69, v72
	v_mov_b32_e32 v71, v73
	v_pk_add_f32 v[68:69], v[68:69], v[70:71]
	s_nop 0
	v_pk_add_f32 v[66:67], v[66:67], v[68:69]
	v_and_b32_e32 v68, 64, v196
	v_add_f32_e32 v66, v66, v67
	v_xor_b32_e32 v67, 16, v196
	v_add_u32_e32 v68, 64, v68
	v_cmp_lt_i32_e32 vcc, v67, v68
	s_nop 1
	v_cndmask_b32_e32 v67, v196, v67, vcc
	v_lshlrev_b32_e32 v67, 2, v67
	ds_bpermute_b32 v67, v67, v66
	s_waitcnt lgkmcnt(0)
	v_add_f32_e32 v66, v66, v67
	v_xor_b32_e32 v67, 32, v196
	v_cmp_lt_i32_e32 vcc, v67, v68
	s_nop 1
	v_cndmask_b32_e32 v67, v196, v67, vcc
	v_lshlrev_b32_e32 v67, 2, v67
	ds_bpermute_b32 v67, v67, v66
	s_waitcnt lgkmcnt(0)
	v_add_f32_e32 v66, v66, v67
	v_fmamk_f32 v66, v66, 0x3c800000, v195
	v_mul_f32_e32 v67, 0x4b800000, v66
	v_cmp_gt_f32_e32 vcc, s2, v66
	s_nop 1
	v_cndmask_b32_e32 v66, v66, v67, vcc
	v_rsq_f32_e32 v66, v66
	s_nop 0
	v_mul_f32_e32 v67, 0x45800000, v66
	v_cndmask_b32_e32 v78, v66, v67, vcc
	v_pk_mul_f32 v[62:63], v[62:63], v[78:79] op_sel_hi:[1,0]
	v_pk_mul_f32 v[64:65], v[64:65], v[78:79] op_sel_hi:[1,0]
	v_pk_mul_f32 v[58:59], v[58:59], v[78:79] op_sel_hi:[1,0]
	v_pk_mul_f32 v[60:61], v[60:61], v[78:79] op_sel_hi:[1,0]
	v_pk_mul_f32 v[54:55], v[54:55], v[78:79] op_sel_hi:[1,0]
	v_pk_mul_f32 v[56:57], v[56:57], v[78:79] op_sel_hi:[1,0]
	v_pk_mul_f32 v[50:51], v[50:51], v[78:79] op_sel_hi:[1,0]
	v_pk_mul_f32 v[52:53], v[52:53], v[78:79] op_sel_hi:[1,0]
	v_pk_mul_f32 v[68:69], v[32:33], v[64:65]
	v_pk_mul_f32 v[66:67], v[30:31], v[62:63]
	v_pk_mul_f32 v[72:73], v[28:29], v[60:61]
	v_pk_mul_f32 v[70:71], v[26:27], v[58:59]
	v_pk_mul_f32 v[76:77], v[48:49], v[56:57]
	v_pk_mul_f32 v[74:75], v[46:47], v[54:55]
	v_pk_mul_f32 v[80:81], v[44:45], v[52:53]
	v_pk_mul_f32 v[78:79], v[42:43], v[50:51]
	s_and_b64 vcc, exec, s[8:9]
	v_or_b32_e32 v52, s33, v189
	s_cbranch_vccnz .LBB0_315
	s_branch .LBB0_306

;     __device__ __forceinline__ void operator()(f32x4 (&acc)[2][2][4][2], const Unit& u, int wr, int wc, int fr, int fq) const {
;     ...
;                 if (is_norm) {
;                     float ss = 0.f;
; #pragma unroll
;                     for (int bj = 0; bj < 2; ++bj)
; #pragma unroll
;                         for (int n = 0; n < 2; ++n) { const f32x4 x = v[bj][n]; ss += (x[0] * x[0] + x[1] * x[1]) + (x[2] * x[2] + x[3] * x[3]); }
;                     ss += __shfl_xor(ss, 16); ss += __shfl_xor(ss, 32);
;                     const float rs = rsqrtf(ss * (1.f / 64.f) + EPS);
; #pragma unroll
;                     for (int bj = 0; bj < 2; ++bj)
; #pragma unroll
;                         for (int n = 0; n < 2; ++n) v[bj][n] = v[bj][n] * rs * gv[bj][n];
.LBB0_318:
	s_and_b64 vcc, exec, s[0:1]
	s_cbranch_vccz .LBB0_335
	v_pk_mul_f32 v[50:51], v[40:41], v[40:41]
	v_pk_mul_f32 v[52:53], v[38:39], v[38:39]
	s_nop 0
	v_pk_mov_b32 v[54:55], v[52:53], v[50:51] op_sel:[1,0]
	v_mov_b32_e32 v53, v51
	v_pk_add_f32 v[50:51], v[54:55], v[52:53]
	v_pk_mul_f32 v[52:53], v[36:37], v[36:37]
	v_pk_mul_f32 v[54:55], v[34:35], v[34:35]
	v_pk_add_f32 v[50:51], v[50:51], v[50:51] op_sel:[0,1] op_sel_hi:[1,0]
	v_pk_mov_b32 v[56:57], v[54:55], v[52:53] op_sel:[1,0]
	v_mov_b32_e32 v55, v53
	v_pk_add_f32 v[52:53], v[56:57], v[54:55]
	v_mul_f32_e32 v54, v18, v18
	v_mul_f32_e32 v55, v19, v19
	v_pk_add_f32 v[52:53], v[52:53], v[52:53] op_sel:[0,1] op_sel_hi:[1,0]
	v_mov_b32_e32 v51, v54
	v_mov_b32_e32 v53, v55
	v_pk_add_f32 v[50:51], v[50:51], v[52:53]
	v_mul_f32_e32 v52, v23, v23
	v_mul_f32_e32 v54, v25, v25
	v_mul_f32_e32 v56, v20, v20
	v_mul_f32_e32 v57, v21, v21
	v_pk_fma_f32 v[52:53], v[22:23], v[22:23], v[52:53] op_sel_hi:[1,1,0]
	v_pk_fma_f32 v[54:55], v[24:25], v[24:25], v[54:55] op_sel_hi:[1,1,0]
	v_mov_b32_e32 v53, v56
	v_mov_b32_e32 v55, v57
	v_pk_add_f32 v[52:53], v[52:53], v[54:55]
	s_nop 0
	v_pk_add_f32 v[50:51], v[50:51], v[52:53]
	v_and_b32_e32 v52, 64, v196
	v_add_f32_e32 v50, v50, v51
	v_xor_b32_e32 v51, 16, v196
	v_add_u32_e32 v52, 64, v52
	v_cmp_lt_i32_e32 vcc, v51, v52
	s_nop 1
	v_cndmask_b32_e32 v51, v196, v51, vcc
	v_lshlrev_b32_e32 v51, 2, v51
	ds_bpermute_b32 v51, v51, v50
	s_waitcnt lgkmcnt(0)
	v_add_f32_e32 v50, v50, v51
	v_xor_b32_e32 v51, 32, v196
	v_cmp_lt_i32_e32 vcc, v51, v52
	s_nop 1
	v_cndmask_b32_e32 v51, v196, v51, vcc
	v_lshlrev_b32_e32 v51, 2, v51
	ds_bpermute_b32 v51, v51, v50
	s_waitcnt lgkmcnt(0)
	v_add_f32_e32 v50, v50, v51
	v_fmamk_f32 v50, v50, 0x3c800000, v195
	v_mul_f32_e32 v51, 0x4b800000, v50
	v_cmp_gt_f32_e32 vcc, s2, v50
	s_nop 1
	v_cndmask_b32_e32 v50, v50, v51, vcc
	v_rsq_f32_e32 v50, v50
	s_nop 0
	v_mul_f32_e32 v51, 0x45800000, v50
	v_cndmask_b32_e32 v62, v50, v51, vcc
	v_pk_mul_f32 v[38:39], v[38:39], v[62:63] op_sel_hi:[1,0]
	v_pk_mul_f32 v[40:41], v[40:41], v[62:63] op_sel_hi:[1,0]
	v_pk_mul_f32 v[34:35], v[34:35], v[62:63] op_sel_hi:[1,0]
	v_pk_mul_f32 v[36:37], v[36:37], v[62:63] op_sel_hi:[1,0]
	v_pk_mul_f32 v[22:23], v[22:23], v[62:63] op_sel_hi:[1,0]
	v_pk_mul_f32 v[24:25], v[24:25], v[62:63] op_sel_hi:[1,0]
	v_pk_mul_f32 v[18:19], v[18:19], v[62:63] op_sel_hi:[1,0]
	v_pk_mul_f32 v[20:21], v[20:21], v[62:63] op_sel_hi:[1,0]
	v_pk_mul_f32 v[52:53], v[32:33], v[40:41]
	v_pk_mul_f32 v[50:51], v[30:31], v[38:39]
	v_pk_mul_f32 v[56:57], v[28:29], v[36:37]
	v_pk_mul_f32 v[54:55], v[26:27], v[34:35]
	v_pk_mul_f32 v[60:61], v[48:49], v[24:25]
	v_pk_mul_f32 v[58:59], v[46:47], v[22:23]
	v_pk_mul_f32 v[64:65], v[44:45], v[20:21]
	v_pk_mul_f32 v[62:63], v[42:43], v[18:19]
	s_and_b64 vcc, exec, s[8:9]
	v_or_b32_e32 v20, s33, v190
	s_cbranch_vccnz .LBB0_345
	s_branch .LBB0_336

;     __device__ __forceinline__ void operator()(f32x4 (&acc)[2][2][4][2], const Unit& u, int wr, int wc, int fr, int fq) const {
;     ...
;                 if (is_norm) {
;                     float ss = 0.f;
; #pragma unroll
;                     for (int bj = 0; bj < 2; ++bj)
; #pragma unroll
;                         for (int n = 0; n < 2; ++n) { const f32x4 x = v[bj][n]; ss += (x[0] * x[0] + x[1] * x[1]) + (x[2] * x[2] + x[3] * x[3]); }
;                     ss += __shfl_xor(ss, 16); ss += __shfl_xor(ss, 32);
;                     const float rs = rsqrtf(ss * (1.f / 64.f) + EPS);
; #pragma unroll
;                     for (int bj = 0; bj < 2; ++bj)
; #pragma unroll
;                         for (int n = 0; n < 2; ++n) v[bj][n] = v[bj][n] * rs * gv[bj][n];
.LBB0_348:
	s_and_b64 vcc, exec, s[0:1]
	s_cbranch_vccz .LBB0_365
	v_pk_mul_f32 v[18:19], v[16:17], v[16:17]
	v_pk_mul_f32 v[20:21], v[14:15], v[14:15]
	s_nop 0
	v_pk_mov_b32 v[22:23], v[20:21], v[18:19] op_sel:[1,0]
	v_mov_b32_e32 v21, v19
	v_pk_add_f32 v[18:19], v[22:23], v[20:21]
	v_pk_mul_f32 v[20:21], v[12:13], v[12:13]
	v_pk_mul_f32 v[22:23], v[10:11], v[10:11]
	v_pk_add_f32 v[18:19], v[18:19], v[18:19] op_sel:[0,1] op_sel_hi:[1,0]
	v_pk_mov_b32 v[24:25], v[22:23], v[20:21] op_sel:[1,0]
	v_mov_b32_e32 v23, v21
	v_pk_add_f32 v[20:21], v[24:25], v[22:23]
	v_mul_f32_e32 v22, v2, v2
	v_mul_f32_e32 v23, v3, v3
	v_pk_add_f32 v[20:21], v[20:21], v[20:21] op_sel:[0,1] op_sel_hi:[1,0]
	v_mov_b32_e32 v19, v22
	v_mov_b32_e32 v21, v23
	v_pk_add_f32 v[18:19], v[18:19], v[20:21]
	v_mul_f32_e32 v20, v7, v7
	v_mul_f32_e32 v22, v9, v9
	v_mul_f32_e32 v24, v4, v4
	v_mul_f32_e32 v25, v5, v5
	v_pk_fma_f32 v[20:21], v[6:7], v[6:7], v[20:21] op_sel_hi:[1,1,0]
	v_pk_fma_f32 v[22:23], v[8:9], v[8:9], v[22:23] op_sel_hi:[1,1,0]
	v_mov_b32_e32 v21, v24
	v_mov_b32_e32 v23, v25
	v_pk_add_f32 v[20:21], v[20:21], v[22:23]
	s_nop 0
	v_pk_add_f32 v[18:19], v[18:19], v[20:21]
	v_and_b32_e32 v20, 64, v196
	v_add_f32_e32 v18, v18, v19
	v_xor_b32_e32 v19, 16, v196
	v_add_u32_e32 v20, 64, v20
	v_cmp_lt_i32_e32 vcc, v19, v20
	s_nop 1
	v_cndmask_b32_e32 v19, v196, v19, vcc
	v_lshlrev_b32_e32 v19, 2, v19
	ds_bpermute_b32 v19, v19, v18
	s_waitcnt lgkmcnt(0)
	v_add_f32_e32 v18, v18, v19
	v_xor_b32_e32 v19, 32, v196
	v_cmp_lt_i32_e32 vcc, v19, v20
	s_nop 1
	v_cndmask_b32_e32 v19, v196, v19, vcc
	v_lshlrev_b32_e32 v19, 2, v19
	ds_bpermute_b32 v19, v19, v18
	s_waitcnt lgkmcnt(0)
	v_add_f32_e32 v18, v18, v19
	v_fmamk_f32 v18, v18, 0x3c800000, v195
	v_mul_f32_e32 v19, 0x4b800000, v18
	v_cmp_gt_f32_e32 vcc, s2, v18
	s_nop 1
	v_cndmask_b32_e32 v18, v18, v19, vcc
	v_rsq_f32_e32 v18, v18
	s_nop 0
	v_mul_f32_e32 v19, 0x45800000, v18
	v_cndmask_b32_e32 v38, v18, v19, vcc
	v_pk_mul_f32 v[14:15], v[14:15], v[38:39] op_sel_hi:[1,0]
	v_pk_mul_f32 v[16:17], v[16:17], v[38:39] op_sel_hi:[1,0]
	v_pk_mul_f32 v[10:11], v[10:11], v[38:39] op_sel_hi:[1,0]
	v_pk_mul_f32 v[12:13], v[12:13], v[38:39] op_sel_hi:[1,0]
	v_pk_mul_f32 v[6:7], v[6:7], v[38:39] op_sel_hi:[1,0]
	v_pk_mul_f32 v[8:9], v[8:9], v[38:39] op_sel_hi:[1,0]
	v_pk_mul_f32 v[2:3], v[2:3], v[38:39] op_sel_hi:[1,0]
	v_pk_mul_f32 v[4:5], v[4:5], v[38:39] op_sel_hi:[1,0]
	v_pk_mul_f32 v[20:21], v[32:33], v[16:17]
	v_pk_mul_f32 v[18:19], v[30:31], v[14:15]
	v_pk_mul_f32 v[24:25], v[28:29], v[12:13]
	v_pk_mul_f32 v[22:23], v[26:27], v[10:11]
	v_pk_mul_f32 v[36:37], v[48:49], v[8:9]
	v_pk_mul_f32 v[34:35], v[46:47], v[6:7]
	v_pk_mul_f32 v[40:41], v[44:45], v[4:5]
	v_pk_mul_f32 v[38:39], v[42:43], v[2:3]
	s_and_b64 vcc, exec, s[8:9]
	v_or_b32_e32 v4, s33, v191
	s_cbranch_vccnz .LBB0_375
	s_branch .LBB0_366
